# tile headers: accumulator zeroing with 64 v_mov_b64 (inline 0) instead of 128 v_mov_b32
# speedup vs baseline: 1.0046x; 1.0014x over previous
; template <class Epi, class Sched, bool ALIGN_EPI = false, bool SP2 = false>
; __device__ __forceinline__ void gemm_phase(PG8_LAS unsigned char* lds, const Gemm g, const Sched& S, const Epi& E) {
;     ...
;         for (int a = 0; a < 2; ++a)
; #pragma unroll
;             for (int b = 0; b < 2; ++b)
; #pragma unroll
;                 for (int m = 0; m < 4; ++m)
; #pragma unroll
;                     for (int n = 0; n < 2; ++n) acc[a][b][m][n] = (f32x4){0.f, 0.f, 0.f, 0.f};
.LBB0_363:
	v_readlane_b32 s38, v252, 59
	v_mov_b32_e32 v161, 0
	v_readlane_b32 s39, v252, 60
	s_andn2_b64 vcc, exec, s[38:39]
	s_waitcnt vmcnt(0)
	s_cbranch_vccnz .Lmy_z0
	s_add_u32 s0, s0, 0x80
	s_addc_u32 s1, s1, 0
	s_add_u32 s72, s86, 0x100
	v_mov_b64_e32 v[40:41], 0
	s_addc_u32 s73, s87, 0
	s_mov_b32 s86, 0
	v_mov_b64_e32 v[42:43], 0
	v_mov_b64_e32 v[104:105], 0
	v_mov_b64_e32 v[106:107], 0
	v_mov_b64_e32 v[8:9], 0
	v_mov_b64_e32 v[10:11], 0
	v_mov_b64_e32 v[72:73], 0
	v_mov_b64_e32 v[74:75], 0
	v_mov_b64_e32 v[16:17], 0
	v_mov_b64_e32 v[18:19], 0
	v_mov_b64_e32 v[80:81], 0
	v_mov_b64_e32 v[82:83], 0
	v_mov_b64_e32 v[24:25], 0
	v_mov_b64_e32 v[26:27], 0
	v_mov_b64_e32 v[88:89], 0
	v_mov_b64_e32 v[90:91], 0
	v_mov_b64_e32 v[44:45], 0
	v_mov_b64_e32 v[46:47], 0
	v_mov_b64_e32 v[108:109], 0
	v_mov_b64_e32 v[110:111], 0
	v_mov_b64_e32 v[12:13], 0
	v_mov_b64_e32 v[14:15], 0
	v_mov_b64_e32 v[76:77], 0
	v_mov_b64_e32 v[78:79], 0
	v_mov_b64_e32 v[20:21], 0
	v_mov_b64_e32 v[22:23], 0
	v_mov_b64_e32 v[84:85], 0
	v_mov_b64_e32 v[86:87], 0
	v_mov_b64_e32 v[28:29], 0
	v_mov_b64_e32 v[30:31], 0
	v_mov_b64_e32 v[92:93], 0
	v_mov_b64_e32 v[94:95], 0
	v_mov_b64_e32 v[64:65], 0
	v_mov_b64_e32 v[66:67], 0
	v_mov_b64_e32 v[112:113], 0
	v_mov_b64_e32 v[114:115], 0
	v_mov_b64_e32 v[32:33], 0
	v_mov_b64_e32 v[34:35], 0
	v_mov_b64_e32 v[96:97], 0
	v_mov_b64_e32 v[98:99], 0
	v_mov_b64_e32 v[48:49], 0
	v_mov_b64_e32 v[50:51], 0
	v_mov_b64_e32 v[146:147], 0
	v_mov_b64_e32 v[148:149], 0
	v_mov_b64_e32 v[56:57], 0
	v_mov_b64_e32 v[58:59], 0
	v_mov_b64_e32 v[154:155], 0
	v_mov_b64_e32 v[156:157], 0
	v_mov_b64_e32 v[68:69], 0
	v_mov_b64_e32 v[70:71], 0
	v_mov_b64_e32 v[116:117], 0
	v_mov_b64_e32 v[118:119], 0
	v_mov_b64_e32 v[36:37], 0
	v_mov_b64_e32 v[38:39], 0
	v_mov_b64_e32 v[100:101], 0
	v_mov_b64_e32 v[102:103], 0
	v_mov_b64_e32 v[52:53], 0
	v_mov_b64_e32 v[54:55], 0
	v_mov_b64_e32 v[150:151], 0
	v_mov_b64_e32 v[152:153], 0
	v_mov_b64_e32 v[60:61], 0
	v_mov_b64_e32 v[62:63], 0
	v_mov_b64_e32 v[158:159], 0
	v_mov_b64_e32 v[160:161], 0

; template <class Epi, class Sched, bool ALIGN_EPI = false, bool SP2 = false>
; __device__ __forceinline__ void gemm_phase(PG8_LAS unsigned char* lds, const Gemm g, const Sched& S, const Epi& E) {
;     ...
;         for (int a = 0; a < 2; ++a)
; #pragma unroll
;             for (int b = 0; b < 2; ++b)
; #pragma unroll
;                 for (int m = 0; m < 4; ++m)
; #pragma unroll
;                     for (int n = 0; n < 2; ++n) acc[a][b][m][n] = (f32x4){0.f, 0.f, 0.f, 0.f};
.LBB0_466:
	v_readlane_b32 s40, v252, 59
	v_mov_b32_e32 v135, 0
	v_readlane_b32 s41, v252, 60
	s_andn2_b64 vcc, exec, s[40:41]
	s_waitcnt vmcnt(0)
	s_cbranch_vccnz .Lmy_z2
	s_add_u32 s0, s0, 0x80
	s_addc_u32 s1, s1, 0
	s_add_u32 s40, s38, 0x100
	v_mov_b64_e32 v[8:9], 0
	s_addc_u32 s41, s39, 0
	s_mov_b32 s38, 0
	v_mov_b64_e32 v[10:11], 0
	v_mov_b64_e32 v[12:13], 0
	v_mov_b64_e32 v[14:15], 0
	v_mov_b64_e32 v[24:25], 0
	v_mov_b64_e32 v[26:27], 0
	v_mov_b64_e32 v[28:29], 0
	v_mov_b64_e32 v[30:31], 0
	v_mov_b64_e32 v[40:41], 0
	v_mov_b64_e32 v[42:43], 0
	v_mov_b64_e32 v[44:45], 0
	v_mov_b64_e32 v[46:47], 0
	v_mov_b64_e32 v[56:57], 0
	v_mov_b64_e32 v[58:59], 0
	v_mov_b64_e32 v[60:61], 0
	v_mov_b64_e32 v[62:63], 0
	v_mov_b64_e32 v[16:17], 0
	v_mov_b64_e32 v[18:19], 0
	v_mov_b64_e32 v[20:21], 0
	v_mov_b64_e32 v[22:23], 0
	v_mov_b64_e32 v[32:33], 0
	v_mov_b64_e32 v[34:35], 0
	v_mov_b64_e32 v[36:37], 0
	v_mov_b64_e32 v[38:39], 0
	v_mov_b64_e32 v[48:49], 0
	v_mov_b64_e32 v[50:51], 0
	v_mov_b64_e32 v[52:53], 0
	v_mov_b64_e32 v[54:55], 0
	v_mov_b64_e32 v[64:65], 0
	v_mov_b64_e32 v[66:67], 0
	v_mov_b64_e32 v[68:69], 0
	v_mov_b64_e32 v[70:71], 0
	v_mov_b64_e32 v[72:73], 0
	v_mov_b64_e32 v[74:75], 0
	v_mov_b64_e32 v[76:77], 0
	v_mov_b64_e32 v[78:79], 0
	v_mov_b64_e32 v[88:89], 0
	v_mov_b64_e32 v[90:91], 0
	v_mov_b64_e32 v[92:93], 0
	v_mov_b64_e32 v[94:95], 0
	v_mov_b64_e32 v[104:105], 0
	v_mov_b64_e32 v[106:107], 0
	v_mov_b64_e32 v[108:109], 0
	v_mov_b64_e32 v[110:111], 0
	v_mov_b64_e32 v[120:121], 0
	v_mov_b64_e32 v[122:123], 0
	v_mov_b64_e32 v[124:125], 0
	v_mov_b64_e32 v[126:127], 0
	v_mov_b64_e32 v[80:81], 0
	v_mov_b64_e32 v[82:83], 0
	v_mov_b64_e32 v[84:85], 0
	v_mov_b64_e32 v[86:87], 0
	v_mov_b64_e32 v[96:97], 0
	v_mov_b64_e32 v[98:99], 0
	v_mov_b64_e32 v[100:101], 0
	v_mov_b64_e32 v[102:103], 0
	v_mov_b64_e32 v[112:113], 0
	v_mov_b64_e32 v[114:115], 0
	v_mov_b64_e32 v[116:117], 0
	v_mov_b64_e32 v[118:119], 0
	v_mov_b64_e32 v[128:129], 0
	v_mov_b64_e32 v[130:131], 0
	v_mov_b64_e32 v[132:133], 0
	v_mov_b64_e32 v[134:135], 0

; template <class Epi, class Sched, bool ALIGN_EPI = false, bool SP2 = false>
; __device__ __forceinline__ void gemm_phase(PG8_LAS unsigned char* lds, const Gemm g, const Sched& S, const Epi& E) {
;     ...
;         for (int a = 0; a < 2; ++a)
; #pragma unroll
;             for (int b = 0; b < 2; ++b)
; #pragma unroll
;                 for (int m = 0; m < 4; ++m)
; #pragma unroll
;                     for (int n = 0; n < 2; ++n) acc[a][b][m][n] = (f32x4){0.f, 0.f, 0.f, 0.f};
.LBB0_499:
	v_readlane_b32 s4, v252, 59
	v_mov_b32_e32 v135, 0
	v_readlane_b32 s5, v252, 60
	s_andn2_b64 vcc, exec, s[4:5]
	s_waitcnt vmcnt(0)
	s_cbranch_vccnz .Lmy_z1
	s_add_u32 s0, s0, 0x80
	s_addc_u32 s1, s1, 0
	s_add_u32 s42, s42, 0x100
	v_mov_b64_e32 v[8:9], 0
	s_addc_u32 s43, s43, 0
	s_mov_b32 s4, 0
	v_mov_b64_e32 v[10:11], 0
	v_mov_b64_e32 v[12:13], 0
	v_mov_b64_e32 v[14:15], 0
	v_mov_b64_e32 v[24:25], 0
	v_mov_b64_e32 v[26:27], 0
	v_mov_b64_e32 v[28:29], 0
	v_mov_b64_e32 v[30:31], 0
	v_mov_b64_e32 v[40:41], 0
	v_mov_b64_e32 v[42:43], 0
	v_mov_b64_e32 v[44:45], 0
	v_mov_b64_e32 v[46:47], 0
	v_mov_b64_e32 v[56:57], 0
	v_mov_b64_e32 v[58:59], 0
	v_mov_b64_e32 v[60:61], 0
	v_mov_b64_e32 v[62:63], 0
	v_mov_b64_e32 v[16:17], 0
	v_mov_b64_e32 v[18:19], 0
	v_mov_b64_e32 v[20:21], 0
	v_mov_b64_e32 v[22:23], 0
	v_mov_b64_e32 v[32:33], 0
	v_mov_b64_e32 v[34:35], 0
	v_mov_b64_e32 v[36:37], 0
	v_mov_b64_e32 v[38:39], 0
	v_mov_b64_e32 v[48:49], 0
	v_mov_b64_e32 v[50:51], 0
	v_mov_b64_e32 v[52:53], 0
	v_mov_b64_e32 v[54:55], 0
	v_mov_b64_e32 v[64:65], 0
	v_mov_b64_e32 v[66:67], 0
	v_mov_b64_e32 v[68:69], 0
	v_mov_b64_e32 v[70:71], 0
	v_mov_b64_e32 v[72:73], 0
	v_mov_b64_e32 v[74:75], 0
	v_mov_b64_e32 v[76:77], 0
	v_mov_b64_e32 v[78:79], 0
	v_mov_b64_e32 v[88:89], 0
	v_mov_b64_e32 v[90:91], 0
	v_mov_b64_e32 v[92:93], 0
	v_mov_b64_e32 v[94:95], 0
	v_mov_b64_e32 v[104:105], 0
	v_mov_b64_e32 v[106:107], 0
	v_mov_b64_e32 v[108:109], 0
	v_mov_b64_e32 v[110:111], 0
	v_mov_b64_e32 v[120:121], 0
	v_mov_b64_e32 v[122:123], 0
	v_mov_b64_e32 v[124:125], 0
	v_mov_b64_e32 v[126:127], 0
	v_mov_b64_e32 v[80:81], 0
	v_mov_b64_e32 v[82:83], 0
	v_mov_b64_e32 v[84:85], 0
	v_mov_b64_e32 v[86:87], 0
	v_mov_b64_e32 v[96:97], 0
	v_mov_b64_e32 v[98:99], 0
	v_mov_b64_e32 v[100:101], 0
	v_mov_b64_e32 v[102:103], 0
	v_mov_b64_e32 v[112:113], 0
	v_mov_b64_e32 v[114:115], 0
	v_mov_b64_e32 v[116:117], 0
	v_mov_b64_e32 v[118:119], 0
	v_mov_b64_e32 v[128:129], 0
	v_mov_b64_e32 v[130:131], 0
	v_mov_b64_e32 v[132:133], 0
	v_mov_b64_e32 v[134:135], 0
